# adds: early L2 write-back on arrival at the 4 remaining grid barriers; write-through stores in SSM step-3, GLU and context-attention epilogues
# baseline (speedup 1.0000x reference)
.LBB0_235:
	s_lshl_b32 s4, s33, 8
	s_add_u32 s4, s20, s4
	s_addc_u32 s5, s21, 0
	v_mov_b32_e32 v1, 0x1000
	v_mov_b32_e32 v3, 1
	buffer_wbl2 sc1
	s_waitcnt vmcnt(0)
	global_atomic_add v3, v1, v3, s[4:5] offset:1024 sc0
	v_cvt_f32_u32_e32 v1, v2
	v_sub_u32_e32 v4, 0, v2
	v_rcp_iflag_f32_e32 v1, v1
	s_nop 0
	v_mul_f32_e32 v1, 0x4f7ffffe, v1
	v_cvt_u32_f32_e32 v1, v1
	v_mul_lo_u32 v4, v4, v1
	v_mul_hi_u32 v4, v1, v4
	v_add_u32_e32 v1, v1, v4
	s_waitcnt vmcnt(0)
	v_mul_hi_u32 v1, v3, v1
	v_mul_lo_u32 v4, v1, v2
	v_sub_u32_e32 v4, v3, v4
	v_add_u32_e32 v5, 1, v1
	v_cmp_ge_u32_e32 vcc, v4, v2
	v_add_u32_e32 v3, 1, v3
	s_nop 0
	v_cndmask_b32_e32 v1, v1, v5, vcc
	v_sub_u32_e32 v5, v4, v2
	v_cndmask_b32_e32 v4, v4, v5, vcc
	v_add_u32_e32 v5, 1, v1
	v_cmp_ge_u32_e32 vcc, v4, v2
	s_nop 1
	v_cndmask_b32_e32 v1, v1, v5, vcc
	v_mul_lo_u32 v4, v2, v1
	v_add_u32_e32 v2, v4, v2
	v_cmp_ne_u32_e32 vcc, v3, v2
	s_and_saveexec_b64 s[6:7], vcc
	s_xor_b64 s[6:7], exec, s[6:7]
	s_cbranch_execz .LBB0_249
	s_waitcnt lgkmcnt(0)
	v_mov_b32_e32 v0, 0x2000
	global_load_dword v0, v0, s[4:5] offset:1024 sc1
	s_add_u32 s14, s4, 0x2400
	s_addc_u32 s15, s5, 0
	s_waitcnt vmcnt(0)
	v_cmp_eq_u32_e32 vcc, v0, v1
	s_and_saveexec_b64 s[8:9], vcc
	s_cbranch_execz .LBB0_248
	v_readlane_b32 s16, v255, 2
	v_readlane_b32 s17, v255, 3
	s_add_u32 s10, s16, 0x4200
	v_readlane_b32 s18, v255, 4
	v_readlane_b32 s19, v255, 5
	s_addc_u32 s11, s17, 0
	s_mov_b32 s28, 1
	s_mov_b64 s[16:17], 0
	v_mov_b32_e32 v0, 0
	s_branch .LBB0_239

.LBB0_487:
	v_readlane_b32 s4, v255, 14
	v_readlane_b32 s5, v255, 15
	v_cvt_f32_u32_e32 v1, v2
	v_sub_u32_e32 v4, 0, v2
	v_rcp_iflag_f32_e32 v1, v1
	s_nop 1
	buffer_wbl2 sc1
	s_waitcnt vmcnt(0)
	global_atomic_add v3, v177, v223, s[4:5] sc0
	v_mul_f32_e32 v1, 0x4f7ffffe, v1
	v_cvt_u32_f32_e32 v1, v1
	v_mul_lo_u32 v4, v4, v1
	v_mul_hi_u32 v4, v1, v4
	v_add_u32_e32 v1, v1, v4
	s_waitcnt vmcnt(0)
	v_mul_hi_u32 v1, v3, v1
	v_mul_lo_u32 v4, v1, v2
	v_sub_u32_e32 v4, v3, v4
	v_add_u32_e32 v5, 1, v1
	v_cmp_ge_u32_e32 vcc, v4, v2
	v_add_u32_e32 v3, 1, v3
	s_nop 0
	v_cndmask_b32_e32 v1, v1, v5, vcc
	v_sub_u32_e32 v5, v4, v2
	v_cndmask_b32_e32 v4, v4, v5, vcc
	v_add_u32_e32 v5, 1, v1
	v_cmp_ge_u32_e32 vcc, v4, v2
	s_nop 1
	v_cndmask_b32_e32 v1, v1, v5, vcc
	v_mul_lo_u32 v4, v2, v1
	v_add_u32_e32 v2, v4, v2
	v_cmp_ne_u32_e32 vcc, v3, v2
	s_and_saveexec_b64 s[4:5], vcc
	s_xor_b64 s[4:5], exec, s[4:5]
	s_cbranch_execz .LBB0_501
	v_readlane_b32 s6, v255, 16
	v_readlane_b32 s7, v255, 17
	s_waitcnt lgkmcnt(0)
	s_nop 3
	global_load_dword v0, v177, s[6:7] sc1
	s_waitcnt vmcnt(0)
	v_cmp_eq_u32_e32 vcc, v0, v1
	s_and_saveexec_b64 s[6:7], vcc
	s_cbranch_execz .LBB0_500
	s_mov_b32 s10, 1
	s_mov_b64 s[18:19], 0
	s_branch .LBB0_491

.LBB0_586:
	s_add_u32 s4, s4, 0x50600000
	v_mov_b32_e32 v128, v220
	s_addc_u32 s5, s5, 0
	s_lshl_b32 s3, s15, 8
	v_cvt_pk_bf16_f32 v124, v124, v125
	v_cvt_pk_bf16_f32 v125, v126, v127
	v_cvt_pk_bf16_f32 v126, v120, v121
	v_cvt_pk_bf16_f32 v127, v122, v123
	s_lshl_b32 s2, s2, 4
	v_readfirstlane_b32 s6, v128
	v_and_or_b32 v129, v128, 15, s3
	s_lshr_b32 s3, s6, 1
	s_lshr_b32 s7, s6, 2
	s_and_b32 s6, s3, 0x60
	v_lshrrev_b32_e32 v130, 1, v128
	s_and_b32 s7, s7, 0xfffffc0
	v_and_or_b32 v120, v130, 16, s6
	v_add_lshl_u32 v129, v129, s7, 4
	v_lshrrev_b32_e32 v122, 4, v120
	v_or_b32_e32 v120, v129, v122
	v_ashrrev_i32_e32 v121, 31, v120
	s_ashr_i32 s3, s2, 31
	v_lshlrev_b64 v[120:121], 11, v[120:121]
	v_lshl_add_u64 v[120:121], s[4:5], 0, v[120:121]
	s_lshl_b64 s[2:3], s[2:3], 1
	v_lshl_add_u64 v[120:121], v[120:121], 0, s[2:3]
	v_and_b32_e32 v176, 16, v128
	v_lshl_add_u64 v[120:121], v[120:121], 0, v[176:177]
	global_store_dwordx4 v[120:121], v[124:127], off sc1
	v_or_b32_e32 v120, 8, v122
	v_cvt_pk_bf16_f32 v116, v116, v117
	v_cvt_pk_bf16_f32 v117, v118, v119
	v_cvt_pk_bf16_f32 v118, v108, v109
	v_or_b32_e32 v108, v120, v129
	v_ashrrev_i32_e32 v109, 31, v108
	v_lshlrev_b64 v[108:109], 11, v[108:109]
	v_lshl_add_u64 v[108:109], s[4:5], 0, v[108:109]
	v_lshl_add_u64 v[108:109], v[108:109], 0, s[2:3]
	v_lshl_add_u64 v[108:109], v[108:109], 0, v[176:177]
	v_cvt_pk_bf16_f32 v119, v110, v111
	global_store_dwordx4 v[108:109], v[116:119], off sc1
	v_cvt_pk_bf16_f32 v108, v112, v113
	v_cvt_pk_bf16_f32 v109, v114, v115
	v_cvt_pk_bf16_f32 v110, v104, v105
	v_cvt_pk_bf16_f32 v111, v106, v107
	s_add_i32 s11, s11, s13
	s_nop 0
	v_or_b32_e32 v116, 0x100, v129
	v_or_b32_e32 v104, v116, v122
	v_ashrrev_i32_e32 v105, 31, v104
	v_lshlrev_b64 v[104:105], 11, v[104:105]
	v_lshl_add_u64 v[104:105], s[4:5], 0, v[104:105]
	v_lshl_add_u64 v[104:105], v[104:105], 0, s[2:3]
	v_lshl_add_u64 v[104:105], v[104:105], 0, v[176:177]
	global_store_dwordx4 v[104:105], v[108:111], off sc1
	v_cvt_pk_bf16_f32 v100, v100, v101
	v_cvt_pk_bf16_f32 v101, v102, v103
	v_cvt_pk_bf16_f32 v102, v92, v93
	v_or_b32_e32 v92, v116, v120
	v_ashrrev_i32_e32 v93, 31, v92
	v_lshlrev_b64 v[92:93], 11, v[92:93]
	v_lshl_add_u64 v[92:93], s[4:5], 0, v[92:93]
	v_lshl_add_u64 v[92:93], v[92:93], 0, s[2:3]
	v_lshl_add_u64 v[92:93], v[92:93], 0, v[176:177]
	v_cvt_pk_bf16_f32 v103, v94, v95
	global_store_dwordx4 v[92:93], v[100:103], off sc1
	v_cvt_pk_bf16_f32 v92, v96, v97
	v_cvt_pk_bf16_f32 v93, v98, v99
	v_cvt_pk_bf16_f32 v94, v88, v89
	v_cvt_pk_bf16_f32 v95, v90, v91
	s_nop 1
	v_or_b32_e32 v100, 0x200, v129
	v_or_b32_e32 v88, v100, v122
	v_ashrrev_i32_e32 v89, 31, v88
	v_lshlrev_b64 v[88:89], 11, v[88:89]
	v_lshl_add_u64 v[88:89], s[4:5], 0, v[88:89]
	v_lshl_add_u64 v[88:89], v[88:89], 0, s[2:3]
	v_lshl_add_u64 v[88:89], v[88:89], 0, v[176:177]
	global_store_dwordx4 v[88:89], v[92:95], off sc1
	v_cvt_pk_bf16_f32 v84, v84, v85
	v_cvt_pk_bf16_f32 v85, v86, v87
	v_cvt_pk_bf16_f32 v86, v76, v77
	v_or_b32_e32 v76, v100, v120
	v_ashrrev_i32_e32 v77, 31, v76
	v_lshlrev_b64 v[76:77], 11, v[76:77]
	v_lshl_add_u64 v[76:77], s[4:5], 0, v[76:77]
	v_lshl_add_u64 v[76:77], v[76:77], 0, s[2:3]
	v_lshl_add_u64 v[76:77], v[76:77], 0, v[176:177]
	v_cvt_pk_bf16_f32 v87, v78, v79
	global_store_dwordx4 v[76:77], v[84:87], off sc1
	v_cvt_pk_bf16_f32 v76, v80, v81
	v_cvt_pk_bf16_f32 v77, v82, v83
	v_cvt_pk_bf16_f32 v78, v72, v73
	v_cvt_pk_bf16_f32 v79, v74, v75
	s_nop 1
	v_or_b32_e32 v84, 0x300, v129
	v_or_b32_e32 v72, v84, v122
	v_ashrrev_i32_e32 v73, 31, v72
	v_lshlrev_b64 v[72:73], 11, v[72:73]
	v_lshl_add_u64 v[72:73], s[4:5], 0, v[72:73]
	v_lshl_add_u64 v[72:73], v[72:73], 0, s[2:3]
	v_lshl_add_u64 v[72:73], v[72:73], 0, v[176:177]
	global_store_dwordx4 v[72:73], v[76:79], off sc1
	v_cvt_pk_bf16_f32 v68, v68, v69
	v_cvt_pk_bf16_f32 v69, v70, v71
	v_cvt_pk_bf16_f32 v70, v64, v65
	v_or_b32_e32 v64, v84, v120
	v_ashrrev_i32_e32 v65, 31, v64
	v_lshlrev_b64 v[64:65], 11, v[64:65]
	v_lshl_add_u64 v[64:65], s[4:5], 0, v[64:65]
	v_lshl_add_u64 v[64:65], v[64:65], 0, s[2:3]
	v_lshl_add_u64 v[64:65], v[64:65], 0, v[176:177]
	v_cvt_pk_bf16_f32 v71, v66, v67
	global_store_dwordx4 v[64:65], v[68:71], off sc1
	v_add_u32_e32 v64, 0x800, v129
	v_cvt_pk_bf16_f32 v60, v60, v61
	v_cvt_pk_bf16_f32 v61, v62, v63
	v_cvt_pk_bf16_f32 v62, v56, v57
	v_or_b32_e32 v56, v64, v122
	v_ashrrev_i32_e32 v57, 31, v56
	v_lshlrev_b64 v[56:57], 11, v[56:57]
	v_lshl_add_u64 v[56:57], s[4:5], 0, v[56:57]
	v_lshl_add_u64 v[56:57], v[56:57], 0, s[2:3]
	v_lshl_add_u64 v[56:57], v[56:57], 0, v[176:177]
	v_cvt_pk_bf16_f32 v63, v58, v59
	global_store_dwordx4 v[56:57], v[60:63], off sc1
	v_cvt_pk_bf16_f32 v52, v52, v53
	v_cvt_pk_bf16_f32 v53, v54, v55
	v_cvt_pk_bf16_f32 v54, v44, v45
	v_or_b32_e32 v44, v64, v120
	v_ashrrev_i32_e32 v45, 31, v44
	v_lshlrev_b64 v[44:45], 11, v[44:45]
	v_lshl_add_u64 v[44:45], s[4:5], 0, v[44:45]
	v_lshl_add_u64 v[44:45], v[44:45], 0, s[2:3]
	v_lshl_add_u64 v[44:45], v[44:45], 0, v[176:177]
	v_cvt_pk_bf16_f32 v55, v46, v47
	global_store_dwordx4 v[44:45], v[52:55], off sc1
	v_cvt_pk_bf16_f32 v44, v48, v49
	v_cvt_pk_bf16_f32 v45, v50, v51
	v_cvt_pk_bf16_f32 v46, v40, v41
	v_cvt_pk_bf16_f32 v47, v42, v43
	s_nop 1
	v_add_u32_e32 v52, 0x900, v129
	v_or_b32_e32 v40, v52, v122
	v_ashrrev_i32_e32 v41, 31, v40
	v_lshlrev_b64 v[40:41], 11, v[40:41]
	v_lshl_add_u64 v[40:41], s[4:5], 0, v[40:41]
	v_lshl_add_u64 v[40:41], v[40:41], 0, s[2:3]
	v_lshl_add_u64 v[40:41], v[40:41], 0, v[176:177]
	global_store_dwordx4 v[40:41], v[44:47], off sc1
	v_cvt_pk_bf16_f32 v36, v36, v37
	v_cvt_pk_bf16_f32 v37, v38, v39
	v_cvt_pk_bf16_f32 v38, v28, v29
	v_or_b32_e32 v28, v52, v120
	v_ashrrev_i32_e32 v29, 31, v28
	v_lshlrev_b64 v[28:29], 11, v[28:29]
	v_lshl_add_u64 v[28:29], s[4:5], 0, v[28:29]
	v_lshl_add_u64 v[28:29], v[28:29], 0, s[2:3]
	v_lshl_add_u64 v[28:29], v[28:29], 0, v[176:177]
	v_cvt_pk_bf16_f32 v39, v30, v31
	global_store_dwordx4 v[28:29], v[36:39], off sc1
	v_cvt_pk_bf16_f32 v28, v32, v33
	v_cvt_pk_bf16_f32 v29, v34, v35
	v_cvt_pk_bf16_f32 v30, v24, v25
	v_cvt_pk_bf16_f32 v31, v26, v27
	s_nop 1
	v_add_u32_e32 v36, 0xa00, v129
	v_or_b32_e32 v24, v36, v122
	v_ashrrev_i32_e32 v25, 31, v24
	v_lshlrev_b64 v[24:25], 11, v[24:25]
	v_lshl_add_u64 v[24:25], s[4:5], 0, v[24:25]
	v_lshl_add_u64 v[24:25], v[24:25], 0, s[2:3]
	v_lshl_add_u64 v[24:25], v[24:25], 0, v[176:177]
	global_store_dwordx4 v[24:25], v[28:31], off sc1
	v_cvt_pk_bf16_f32 v20, v20, v21
	v_cvt_pk_bf16_f32 v21, v22, v23
	v_cvt_pk_bf16_f32 v22, v12, v13
	v_or_b32_e32 v12, v36, v120
	v_ashrrev_i32_e32 v13, 31, v12
	v_lshlrev_b64 v[12:13], 11, v[12:13]
	v_lshl_add_u64 v[12:13], s[4:5], 0, v[12:13]
	v_lshl_add_u64 v[12:13], v[12:13], 0, s[2:3]
	v_lshl_add_u64 v[12:13], v[12:13], 0, v[176:177]
	v_cvt_pk_bf16_f32 v23, v14, v15
	global_store_dwordx4 v[12:13], v[20:23], off sc1
	v_cvt_pk_bf16_f32 v12, v16, v17
	v_cvt_pk_bf16_f32 v13, v18, v19
	v_cvt_pk_bf16_f32 v14, v8, v9
	v_cvt_pk_bf16_f32 v15, v10, v11
	s_nop 1
	v_add_u32_e32 v20, 0xb00, v129
	v_or_b32_e32 v8, v20, v122
	v_ashrrev_i32_e32 v9, 31, v8
	v_lshlrev_b64 v[8:9], 11, v[8:9]
	v_lshl_add_u64 v[8:9], s[4:5], 0, v[8:9]
	v_lshl_add_u64 v[8:9], v[8:9], 0, s[2:3]
	v_lshl_add_u64 v[8:9], v[8:9], 0, v[176:177]
	global_store_dwordx4 v[8:9], v[12:15], off sc1
	v_cvt_pk_bf16_f32 v4, v4, v5
	v_cvt_pk_bf16_f32 v5, v6, v7
	v_cvt_pk_bf16_f32 v6, v0, v1
	v_or_b32_e32 v0, v20, v120
	v_ashrrev_i32_e32 v1, 31, v0
	v_lshlrev_b64 v[0:1], 11, v[0:1]
	v_lshl_add_u64 v[0:1], s[4:5], 0, v[0:1]
	v_lshl_add_u64 v[0:1], v[0:1], 0, s[2:3]
	v_lshl_add_u64 v[0:1], v[0:1], 0, v[176:177]
	v_cvt_pk_bf16_f32 v7, v2, v3
	global_store_dwordx4 v[0:1], v[4:7], off sc1
	s_waitcnt vmcnt(0)
	v_readlane_b32 s2, v255, 39
	s_add_i32 s10, s10, s2
	s_cmpk_gt_i32 s11, 0xff
	s_barrier
	s_cbranch_scc1 .LBB0_582

.LBB0_605:
	v_readlane_b32 s4, v255, 14
	v_readlane_b32 s5, v255, 15
	v_cvt_f32_u32_e32 v1, v2
	v_sub_u32_e32 v4, 0, v2
	v_rcp_iflag_f32_e32 v1, v1
	s_nop 1
	buffer_wbl2 sc1
	s_waitcnt vmcnt(0)
	global_atomic_add v3, v177, v223, s[4:5] sc0
	v_mul_f32_e32 v1, 0x4f7ffffe, v1
	v_cvt_u32_f32_e32 v1, v1
	v_mul_lo_u32 v4, v4, v1
	v_mul_hi_u32 v4, v1, v4
	v_add_u32_e32 v1, v1, v4
	s_waitcnt vmcnt(0)
	v_mul_hi_u32 v1, v3, v1
	v_mul_lo_u32 v4, v1, v2
	v_sub_u32_e32 v4, v3, v4
	v_add_u32_e32 v5, 1, v1
	v_cmp_ge_u32_e32 vcc, v4, v2
	v_add_u32_e32 v3, 1, v3
	s_nop 0
	v_cndmask_b32_e32 v1, v1, v5, vcc
	v_sub_u32_e32 v5, v4, v2
	v_cndmask_b32_e32 v4, v4, v5, vcc
	v_add_u32_e32 v5, 1, v1
	v_cmp_ge_u32_e32 vcc, v4, v2
	s_nop 1
	v_cndmask_b32_e32 v1, v1, v5, vcc
	v_mul_lo_u32 v4, v2, v1
	v_add_u32_e32 v2, v4, v2
	v_cmp_ne_u32_e32 vcc, v3, v2
	s_and_saveexec_b64 s[4:5], vcc
	s_xor_b64 s[4:5], exec, s[4:5]
	s_cbranch_execz .LBB0_619
	v_readlane_b32 s6, v255, 16
	v_readlane_b32 s7, v255, 17
	s_waitcnt lgkmcnt(0)
	s_nop 3
	global_load_dword v0, v177, s[6:7] sc1
	s_waitcnt vmcnt(0)
	v_cmp_eq_u32_e32 vcc, v0, v1
	s_and_saveexec_b64 s[6:7], vcc
	s_cbranch_execz .LBB0_618
	s_mov_b32 s10, 1
	s_mov_b64 s[8:9], 0
	s_branch .LBB0_609

.LBB0_737:
	s_or_b64 exec, exec, s[6:7]
	s_lshl_b32 s2, s8, 1
	s_add_u32 s4, s25, s2
	s_addc_u32 s5, s26, 0
	v_lshrrev_b32_e32 v112, 4, v166
	v_lshl_add_u64 v[64:65], s[4:5], 0, v[176:177]
	v_or_b32_e32 v110, v112, v165
	v_lshl_add_u64 v[64:65], v[64:65], 0, s[66:67]
	s_waitcnt lgkmcnt(0)
	v_mad_i64_i32 v[66:67], s[4:5], v110, s45, v[64:65]
	v_or_b32_e32 v108, 4, v110
	v_or_b32_e32 v106, 8, v110
	v_mad_i64_i32 v[68:69], s[4:5], v108, s45, v[64:65]
	global_load_dwordx4 v[92:95], v[66:67], off
	global_load_dwordx4 v[88:91], v[68:69], off
	v_mad_i64_i32 v[66:67], s[4:5], v106, s45, v[64:65]
	v_or_b32_e32 v104, 12, v110
	v_or_b32_e32 v102, 16, v110
	v_mad_i64_i32 v[68:69], s[4:5], v104, s45, v[64:65]
	global_load_dwordx4 v[84:87], v[66:67], off
	global_load_dwordx4 v[80:83], v[68:69], off
	v_mad_i64_i32 v[66:67], s[4:5], v102, s45, v[64:65]
	v_or_b32_e32 v100, 20, v110
	v_lshl_add_u32 v99, v162, 4, v161
	v_mad_i64_i32 v[68:69], s[4:5], v100, s45, v[64:65]
	global_load_dwordx4 v[76:79], v[66:67], off
	global_load_dwordx4 v[72:75], v[68:69], off
	ds_read_b32 v101, v99
	s_movk_i32 s3, 0x2200
	v_mul_lo_u32 v97, v164, s3
	v_or_b32_e32 v98, 24, v110
	v_or_b32_e32 v96, 28, v110
	s_waitcnt lgkmcnt(0)
	v_rcp_f32_e32 v101, v101
	v_add_u32_e32 v97, s33, v97
	v_mad_i64_i32 v[66:67], s[4:5], v98, s45, v[64:65]
	v_mad_i64_i32 v[64:65], s[4:5], v96, s45, v[64:65]
	v_lshl_add_u32 v103, v163, 1, v97
	s_movk_i32 s3, 0x440
	v_mul_f32_e32 v0, v0, v101
	global_load_dwordx4 v[68:71], v[66:67], off
	s_nop 0
	global_load_dwordx4 v[64:67], v[64:65], off
	v_mad_u32_u24 v105, v162, s3, v103
	v_cvt_pk_bf16_f32 v0, v0, v177
	ds_write_b16 v105, v0
	v_mul_f32_e32 v0, v16, v101
	v_cvt_pk_bf16_f32 v0, v0, v177
	ds_write_b16 v105, v0 offset:64
	v_mul_f32_e32 v0, v32, v101
	v_cvt_pk_bf16_f32 v0, v0, v177
	ds_write_b16 v105, v0 offset:128
	v_mul_f32_e32 v0, v48, v101
	v_cvt_pk_bf16_f32 v0, v0, v177
	ds_read_b32 v16, v99 offset:4
	ds_write_b16 v105, v0 offset:192
	v_lshl_or_b32 v0, v162, 2, 1
	s_movk_i32 s3, 0x110
	v_mad_u32_u24 v0, v0, s3, v103
	s_waitcnt lgkmcnt(1)
	v_rcp_f32_e32 v16, v16
	s_lshl_b64 s[4:5], s[20:21], 21
	s_add_u32 s3, s18, s4
	s_addc_u32 s4, s19, s5
	v_mul_f32_e32 v1, v1, v16
	v_cvt_pk_bf16_f32 v1, v1, v177
	ds_write_b16 v0, v1
	v_mul_f32_e32 v1, v17, v16
	v_cvt_pk_bf16_f32 v1, v1, v177
	ds_write_b16 v0, v1 offset:64
	v_mul_f32_e32 v1, v33, v16
	v_cvt_pk_bf16_f32 v1, v1, v177
	ds_write_b16 v0, v1 offset:128
	v_mul_f32_e32 v1, v49, v16
	v_cvt_pk_bf16_f32 v1, v1, v177
	ds_read_b32 v16, v99 offset:8
	ds_write_b16 v0, v1 offset:192
	s_add_u32 s2, s3, s2
	s_addc_u32 s3, s4, 0
	v_ashrrev_i32_e32 v111, 31, v110
	s_waitcnt lgkmcnt(1)
	v_rcp_f32_e32 v16, v16
	v_ashrrev_i32_e32 v109, 31, v108
	v_ashrrev_i32_e32 v107, 31, v106
	v_ashrrev_i32_e32 v105, 31, v104
	v_mul_f32_e32 v1, v2, v16
	v_cvt_pk_bf16_f32 v1, v1, v177
	ds_write_b16 v0, v1 offset:272
	v_mul_f32_e32 v1, v18, v16
	v_cvt_pk_bf16_f32 v1, v1, v177
	ds_write_b16 v0, v1 offset:336
	v_mul_f32_e32 v1, v34, v16
	v_cvt_pk_bf16_f32 v1, v1, v177
	ds_write_b16 v0, v1 offset:400
	v_mul_f32_e32 v1, v50, v16
	v_cvt_pk_bf16_f32 v1, v1, v177
	ds_read_b32 v2, v99 offset:12
	ds_write_b16 v0, v1 offset:464
	v_ashrrev_i32_e32 v103, 31, v102
	v_ashrrev_i32_e32 v101, 31, v100
	s_add_i32 s24, s24, s83
	s_waitcnt lgkmcnt(1)
	v_rcp_f32_e32 v2, v2
	s_nop 0
	v_mul_f32_e32 v1, v3, v2
	v_cvt_pk_bf16_f32 v1, v1, v177
	ds_write_b16 v0, v1 offset:544
	v_mul_f32_e32 v1, v19, v2
	v_cvt_pk_bf16_f32 v1, v1, v177
	ds_write_b16 v0, v1 offset:608
	v_mul_f32_e32 v1, v35, v2
	v_cvt_pk_bf16_f32 v1, v1, v177
	ds_write_b16 v0, v1 offset:672
	v_mul_f32_e32 v1, v51, v2
	v_cvt_pk_bf16_f32 v1, v1, v177
	ds_write_b16 v0, v1 offset:736
	ds_read_b32 v1, v99 offset:32
	s_waitcnt lgkmcnt(0)
	v_rcp_f32_e32 v1, v1
	s_nop 0
	v_mul_f32_e32 v2, v4, v1
	v_cvt_pk_bf16_f32 v2, v2, v177
	ds_write_b16 v0, v2 offset:1904
	v_mul_f32_e32 v2, v20, v1
	v_cvt_pk_bf16_f32 v2, v2, v177
	ds_write_b16 v0, v2 offset:1968
	v_mul_f32_e32 v2, v36, v1
	v_cvt_pk_bf16_f32 v2, v2, v177
	v_mul_f32_e32 v1, v52, v1
	ds_write_b16 v0, v2 offset:2032
	v_cvt_pk_bf16_f32 v1, v1, v177
	ds_read_b32 v2, v99 offset:36
	ds_write_b16 v0, v1 offset:2096
	s_waitcnt lgkmcnt(1)
	v_rcp_f32_e32 v2, v2
	s_nop 0
	v_mul_f32_e32 v1, v5, v2
	v_cvt_pk_bf16_f32 v1, v1, v177
	ds_write_b16 v0, v1 offset:2176
	v_mul_f32_e32 v1, v21, v2
	v_cvt_pk_bf16_f32 v1, v1, v177
	ds_write_b16 v0, v1 offset:2240
	v_mul_f32_e32 v1, v37, v2
	v_cvt_pk_bf16_f32 v1, v1, v177
	ds_write_b16 v0, v1 offset:2304
	v_mul_f32_e32 v1, v53, v2
	v_cvt_pk_bf16_f32 v1, v1, v177
	ds_read_b32 v2, v99 offset:40
	ds_write_b16 v0, v1 offset:2368
	s_waitcnt lgkmcnt(1)
	v_rcp_f32_e32 v2, v2
	s_nop 0
	v_mul_f32_e32 v1, v6, v2
	v_cvt_pk_bf16_f32 v1, v1, v177
	ds_write_b16 v0, v1 offset:2448
	v_mul_f32_e32 v1, v22, v2
	v_cvt_pk_bf16_f32 v1, v1, v177
	ds_write_b16 v0, v1 offset:2512
	v_mul_f32_e32 v1, v38, v2
	v_cvt_pk_bf16_f32 v1, v1, v177
	ds_write_b16 v0, v1 offset:2576
	v_mul_f32_e32 v1, v54, v2
	v_cvt_pk_bf16_f32 v1, v1, v177
	ds_read_b32 v2, v99 offset:44
	ds_write_b16 v0, v1 offset:2640
	s_waitcnt vmcnt(7)
	v_lshlrev_b32_e32 v6, 16, v92
	s_waitcnt lgkmcnt(1)
	v_rcp_f32_e32 v2, v2
	s_nop 0
	v_mul_f32_e32 v1, v7, v2
	v_cvt_pk_bf16_f32 v1, v1, v177
	ds_write_b16 v0, v1 offset:2720
	v_mul_f32_e32 v1, v23, v2
	v_cvt_pk_bf16_f32 v1, v1, v177
	ds_write_b16 v0, v1 offset:2784
	v_mul_f32_e32 v1, v39, v2
	v_cvt_pk_bf16_f32 v1, v1, v177
	ds_write_b16 v0, v1 offset:2848
	v_mul_f32_e32 v1, v55, v2
	v_cvt_pk_bf16_f32 v1, v1, v177
	ds_write_b16 v0, v1 offset:2912
	ds_read_b32 v1, v99 offset:64
	s_waitcnt lgkmcnt(0)
	v_rcp_f32_e32 v1, v1
	s_nop 0
	v_mul_f32_e32 v2, v8, v1
	v_cvt_pk_bf16_f32 v2, v2, v177
	ds_write_b16 v0, v2 offset:4080
	v_mul_f32_e32 v2, v24, v1
	v_cvt_pk_bf16_f32 v2, v2, v177
	ds_write_b16 v0, v2 offset:4144
	v_mul_f32_e32 v2, v40, v1
	v_cvt_pk_bf16_f32 v2, v2, v177
	v_mul_f32_e32 v1, v56, v1
	ds_write_b16 v0, v2 offset:4208
	v_cvt_pk_bf16_f32 v1, v1, v177
	ds_read_b32 v2, v99 offset:68
	ds_write_b16 v0, v1 offset:4272
	s_waitcnt lgkmcnt(1)
	v_rcp_f32_e32 v2, v2
	s_nop 0
	v_mul_f32_e32 v1, v9, v2
	v_cvt_pk_bf16_f32 v1, v1, v177
	ds_write_b16 v0, v1 offset:4352
	v_mul_f32_e32 v1, v25, v2
	v_cvt_pk_bf16_f32 v1, v1, v177
	ds_write_b16 v0, v1 offset:4416
	v_mul_f32_e32 v1, v41, v2
	v_cvt_pk_bf16_f32 v1, v1, v177
	ds_write_b16 v0, v1 offset:4480
	v_mul_f32_e32 v1, v57, v2
	v_cvt_pk_bf16_f32 v1, v1, v177
	ds_read_b32 v2, v99 offset:72
	ds_write_b16 v0, v1 offset:4544
	s_waitcnt lgkmcnt(1)
	v_rcp_f32_e32 v2, v2
	s_nop 0
	v_mul_f32_e32 v1, v10, v2
	v_cvt_pk_bf16_f32 v1, v1, v177
	ds_write_b16 v0, v1 offset:4624
	v_mul_f32_e32 v1, v26, v2
	v_cvt_pk_bf16_f32 v1, v1, v177
	ds_write_b16 v0, v1 offset:4688
	v_mul_f32_e32 v1, v42, v2
	v_cvt_pk_bf16_f32 v1, v1, v177
	ds_write_b16 v0, v1 offset:4752
	v_mul_f32_e32 v1, v58, v2
	v_cvt_pk_bf16_f32 v1, v1, v177
	ds_read_b32 v2, v99 offset:76
	ds_write_b16 v0, v1 offset:4816
	s_waitcnt lgkmcnt(1)
	v_rcp_f32_e32 v2, v2
	s_nop 0
	v_mul_f32_e32 v1, v11, v2
	v_cvt_pk_bf16_f32 v1, v1, v177
	ds_write_b16 v0, v1 offset:4896
	v_mul_f32_e32 v1, v27, v2
	v_cvt_pk_bf16_f32 v1, v1, v177
	ds_write_b16 v0, v1 offset:4960
	v_mul_f32_e32 v1, v43, v2
	v_cvt_pk_bf16_f32 v1, v1, v177
	ds_write_b16 v0, v1 offset:5024
	v_mul_f32_e32 v1, v59, v2
	v_cvt_pk_bf16_f32 v1, v1, v177
	ds_write_b16 v0, v1 offset:5088
	ds_read_b32 v1, v99 offset:96
	v_lshlrev_b64 v[10:11], 13, v[110:111]
	s_waitcnt lgkmcnt(0)
	v_rcp_f32_e32 v1, v1
	s_nop 0
	v_mul_f32_e32 v2, v12, v1
	v_cvt_pk_bf16_f32 v2, v2, v177
	ds_write_b16 v0, v2 offset:6256
	v_mul_f32_e32 v2, v28, v1
	v_cvt_pk_bf16_f32 v2, v2, v177
	ds_write_b16 v0, v2 offset:6320
	v_mul_f32_e32 v2, v44, v1
	v_cvt_pk_bf16_f32 v2, v2, v177
	v_mul_f32_e32 v1, v60, v1
	ds_write_b16 v0, v2 offset:6384
	v_cvt_pk_bf16_f32 v1, v1, v177
	ds_read_b32 v2, v99 offset:100
	ds_write_b16 v0, v1 offset:6448
	s_waitcnt lgkmcnt(1)
	v_rcp_f32_e32 v2, v2
	s_nop 0
	v_mul_f32_e32 v1, v13, v2
	v_cvt_pk_bf16_f32 v1, v1, v177
	ds_write_b16 v0, v1 offset:6528
	v_mul_f32_e32 v1, v29, v2
	v_cvt_pk_bf16_f32 v1, v1, v177
	ds_write_b16 v0, v1 offset:6592
	v_mul_f32_e32 v1, v45, v2
	v_cvt_pk_bf16_f32 v1, v1, v177
	ds_write_b16 v0, v1 offset:6656
	v_mul_f32_e32 v1, v61, v2
	v_cvt_pk_bf16_f32 v1, v1, v177
	ds_read_b32 v2, v99 offset:104
	ds_write_b16 v0, v1 offset:6720
	s_waitcnt lgkmcnt(1)
	v_rcp_f32_e32 v2, v2
	s_nop 0
	v_mul_f32_e32 v1, v14, v2
	v_cvt_pk_bf16_f32 v1, v1, v177
	ds_write_b16 v0, v1 offset:6800
	v_mul_f32_e32 v1, v30, v2
	v_cvt_pk_bf16_f32 v1, v1, v177
	ds_write_b16 v0, v1 offset:6864
	v_mul_f32_e32 v1, v46, v2
	v_cvt_pk_bf16_f32 v1, v1, v177
	ds_write_b16 v0, v1 offset:6928
	v_mul_f32_e32 v1, v62, v2
	v_cvt_pk_bf16_f32 v1, v1, v177
	ds_read_b32 v2, v99 offset:108
	ds_write_b16 v0, v1 offset:6992
	v_ashrrev_i32_e32 v99, 31, v98
	s_waitcnt lgkmcnt(1)
	v_rcp_f32_e32 v2, v2
	s_nop 0
	v_mul_f32_e32 v1, v15, v2
	v_cvt_pk_bf16_f32 v1, v1, v177
	ds_write_b16 v0, v1 offset:7072
	v_mul_f32_e32 v1, v31, v2
	v_cvt_pk_bf16_f32 v1, v1, v177
	ds_write_b16 v0, v1 offset:7136
	v_mul_f32_e32 v1, v47, v2
	v_cvt_pk_bf16_f32 v1, v1, v177
	ds_write_b16 v0, v1 offset:7200
	v_mul_f32_e32 v1, v63, v2
	v_cvt_pk_bf16_f32 v1, v1, v177
	ds_write_b16 v0, v1 offset:7264
	v_mul_u32_u24_e32 v0, 0x110, v112
	s_waitcnt lgkmcnt(0)
	v_add3_u32 v12, v97, v176, v0
	ds_read_b128 v[2:5], v12
	v_lshl_add_u64 v[0:1], s[2:3], 0, v[176:177]
	v_lshl_add_u64 v[0:1], v[0:1], 0, s[60:61]
	v_lshl_add_u64 v[10:11], v[0:1], 0, v[10:11]
	v_ashrrev_i32_e32 v97, 31, v96
	s_waitcnt lgkmcnt(0)
	v_lshlrev_b32_e32 v7, 16, v2
	v_mul_f32_e32 v6, v7, v6
	v_and_b32_e32 v2, 0xffff0000, v2
	v_and_b32_e32 v7, 0xffff0000, v92
	v_mul_f32_e32 v2, v2, v7
	v_cvt_pk_bf16_f32 v2, v6, v2
	v_lshlrev_b32_e32 v6, 16, v93
	v_lshlrev_b32_e32 v7, 16, v3
	v_mul_f32_e32 v6, v7, v6
	v_and_b32_e32 v3, 0xffff0000, v3
	v_and_b32_e32 v7, 0xffff0000, v93
	v_mul_f32_e32 v3, v3, v7
	v_cvt_pk_bf16_f32 v3, v6, v3
	v_lshlrev_b32_e32 v6, 16, v94
	v_lshlrev_b32_e32 v7, 16, v4
	v_mul_f32_e32 v6, v7, v6
	v_and_b32_e32 v4, 0xffff0000, v4
	v_and_b32_e32 v7, 0xffff0000, v94
	v_mul_f32_e32 v4, v4, v7
	v_cvt_pk_bf16_f32 v4, v6, v4
	v_lshlrev_b32_e32 v6, 16, v95
	v_lshlrev_b32_e32 v7, 16, v5
	v_mul_f32_e32 v6, v7, v6
	v_and_b32_e32 v5, 0xffff0000, v5
	v_and_b32_e32 v7, 0xffff0000, v95
	v_mul_f32_e32 v5, v5, v7
	v_cvt_pk_bf16_f32 v5, v6, v5
	ds_read_b128 v[6:9], v12 offset:1088
	global_store_dwordx4 v[10:11], v[2:5], off sc1
	v_lshlrev_b64 v[10:11], 13, v[108:109]
	v_lshl_add_u64 v[10:11], v[0:1], 0, v[10:11]
	s_waitcnt vmcnt(7)
	v_lshlrev_b32_e32 v2, 16, v88
	s_waitcnt lgkmcnt(0)
	v_lshlrev_b32_e32 v3, 16, v6
	v_mul_f32_e32 v2, v3, v2
	v_and_b32_e32 v3, 0xffff0000, v6
	v_and_b32_e32 v4, 0xffff0000, v88
	v_mul_f32_e32 v3, v3, v4
	v_cvt_pk_bf16_f32 v2, v2, v3
	v_lshlrev_b32_e32 v3, 16, v89
	v_lshlrev_b32_e32 v4, 16, v7
	v_mul_f32_e32 v3, v4, v3
	v_and_b32_e32 v4, 0xffff0000, v7
	v_and_b32_e32 v5, 0xffff0000, v89
	v_mul_f32_e32 v4, v4, v5
	v_cvt_pk_bf16_f32 v3, v3, v4
	v_lshlrev_b32_e32 v4, 16, v90
	v_lshlrev_b32_e32 v5, 16, v8
	v_mul_f32_e32 v4, v5, v4
	v_and_b32_e32 v5, 0xffff0000, v8
	v_and_b32_e32 v6, 0xffff0000, v90
	v_mul_f32_e32 v5, v5, v6
	v_cvt_pk_bf16_f32 v4, v4, v5
	v_lshlrev_b32_e32 v5, 16, v91
	v_lshlrev_b32_e32 v6, 16, v9
	v_mul_f32_e32 v5, v6, v5
	v_and_b32_e32 v6, 0xffff0000, v9
	v_and_b32_e32 v7, 0xffff0000, v91
	v_mul_f32_e32 v6, v6, v7
	v_cvt_pk_bf16_f32 v5, v5, v6
	ds_read_b128 v[6:9], v12 offset:2176
	global_store_dwordx4 v[10:11], v[2:5], off sc1
	v_lshlrev_b64 v[10:11], 13, v[106:107]
	v_lshl_add_u64 v[10:11], v[0:1], 0, v[10:11]
	s_waitcnt vmcnt(7)
	v_lshlrev_b32_e32 v2, 16, v84
	s_waitcnt lgkmcnt(0)
	v_lshlrev_b32_e32 v3, 16, v6
	v_mul_f32_e32 v2, v3, v2
	v_and_b32_e32 v3, 0xffff0000, v6
	v_and_b32_e32 v4, 0xffff0000, v84
	v_mul_f32_e32 v3, v3, v4
	v_cvt_pk_bf16_f32 v2, v2, v3
	v_lshlrev_b32_e32 v3, 16, v85
	v_lshlrev_b32_e32 v4, 16, v7
	v_mul_f32_e32 v3, v4, v3
	v_and_b32_e32 v4, 0xffff0000, v7
	v_and_b32_e32 v5, 0xffff0000, v85
	v_mul_f32_e32 v4, v4, v5
	v_cvt_pk_bf16_f32 v3, v3, v4
	v_lshlrev_b32_e32 v4, 16, v86
	v_lshlrev_b32_e32 v5, 16, v8
	v_mul_f32_e32 v4, v5, v4
	v_and_b32_e32 v5, 0xffff0000, v8
	v_and_b32_e32 v6, 0xffff0000, v86
	v_mul_f32_e32 v5, v5, v6
	v_cvt_pk_bf16_f32 v4, v4, v5
	v_lshlrev_b32_e32 v5, 16, v87
	v_lshlrev_b32_e32 v6, 16, v9
	v_mul_f32_e32 v5, v6, v5
	v_and_b32_e32 v6, 0xffff0000, v9
	v_and_b32_e32 v7, 0xffff0000, v87
	v_mul_f32_e32 v6, v6, v7
	v_cvt_pk_bf16_f32 v5, v5, v6
	ds_read_b128 v[6:9], v12 offset:3264
	global_store_dwordx4 v[10:11], v[2:5], off sc1
	v_lshlrev_b64 v[10:11], 13, v[104:105]
	v_lshl_add_u64 v[10:11], v[0:1], 0, v[10:11]
	s_waitcnt vmcnt(7)
	v_lshlrev_b32_e32 v2, 16, v80
	s_waitcnt lgkmcnt(0)
	v_lshlrev_b32_e32 v3, 16, v6
	v_mul_f32_e32 v2, v3, v2
	v_and_b32_e32 v3, 0xffff0000, v6
	v_and_b32_e32 v4, 0xffff0000, v80
	v_mul_f32_e32 v3, v3, v4
	v_cvt_pk_bf16_f32 v2, v2, v3
	v_lshlrev_b32_e32 v3, 16, v81
	v_lshlrev_b32_e32 v4, 16, v7
	v_mul_f32_e32 v3, v4, v3
	v_and_b32_e32 v4, 0xffff0000, v7
	v_and_b32_e32 v5, 0xffff0000, v81
	v_mul_f32_e32 v4, v4, v5
	v_cvt_pk_bf16_f32 v3, v3, v4
	v_lshlrev_b32_e32 v4, 16, v82
	v_lshlrev_b32_e32 v5, 16, v8
	v_mul_f32_e32 v4, v5, v4
	v_and_b32_e32 v5, 0xffff0000, v8
	v_and_b32_e32 v6, 0xffff0000, v82
	v_mul_f32_e32 v5, v5, v6
	v_cvt_pk_bf16_f32 v4, v4, v5
	v_lshlrev_b32_e32 v5, 16, v83
	v_lshlrev_b32_e32 v6, 16, v9
	v_mul_f32_e32 v5, v6, v5
	v_and_b32_e32 v6, 0xffff0000, v9
	v_and_b32_e32 v7, 0xffff0000, v83
	v_mul_f32_e32 v6, v6, v7
	v_cvt_pk_bf16_f32 v5, v5, v6
	ds_read_b128 v[6:9], v12 offset:4352
	global_store_dwordx4 v[10:11], v[2:5], off sc1
	v_lshlrev_b64 v[10:11], 13, v[102:103]
	v_lshl_add_u64 v[10:11], v[0:1], 0, v[10:11]
	s_waitcnt vmcnt(7)
	v_lshlrev_b32_e32 v2, 16, v76
	s_waitcnt lgkmcnt(0)
	v_lshlrev_b32_e32 v3, 16, v6
	v_mul_f32_e32 v2, v3, v2
	v_and_b32_e32 v3, 0xffff0000, v6
	v_and_b32_e32 v4, 0xffff0000, v76
	v_mul_f32_e32 v3, v3, v4
	v_cvt_pk_bf16_f32 v2, v2, v3
	v_lshlrev_b32_e32 v3, 16, v77
	v_lshlrev_b32_e32 v4, 16, v7
	v_mul_f32_e32 v3, v4, v3
	v_and_b32_e32 v4, 0xffff0000, v7
	v_and_b32_e32 v5, 0xffff0000, v77
	v_mul_f32_e32 v4, v4, v5
	v_cvt_pk_bf16_f32 v3, v3, v4
	v_lshlrev_b32_e32 v4, 16, v78
	v_lshlrev_b32_e32 v5, 16, v8
	v_mul_f32_e32 v4, v5, v4
	v_and_b32_e32 v5, 0xffff0000, v8
	v_and_b32_e32 v6, 0xffff0000, v78
	v_mul_f32_e32 v5, v5, v6
	v_cvt_pk_bf16_f32 v4, v4, v5
	v_lshlrev_b32_e32 v5, 16, v79
	v_lshlrev_b32_e32 v6, 16, v9
	v_mul_f32_e32 v5, v6, v5
	v_and_b32_e32 v6, 0xffff0000, v9
	v_and_b32_e32 v7, 0xffff0000, v79
	v_mul_f32_e32 v6, v6, v7
	v_cvt_pk_bf16_f32 v5, v5, v6
	ds_read_b128 v[6:9], v12 offset:5440
	global_store_dwordx4 v[10:11], v[2:5], off sc1
	v_lshlrev_b64 v[10:11], 13, v[100:101]
	v_lshl_add_u64 v[10:11], v[0:1], 0, v[10:11]
	s_waitcnt vmcnt(7)
	v_lshlrev_b32_e32 v2, 16, v72
	s_waitcnt lgkmcnt(0)
	v_lshlrev_b32_e32 v3, 16, v6
	v_mul_f32_e32 v2, v3, v2
	v_and_b32_e32 v3, 0xffff0000, v6
	v_and_b32_e32 v4, 0xffff0000, v72
	v_mul_f32_e32 v3, v3, v4
	v_cvt_pk_bf16_f32 v2, v2, v3
	v_lshlrev_b32_e32 v3, 16, v73
	v_lshlrev_b32_e32 v4, 16, v7
	v_mul_f32_e32 v3, v4, v3
	v_and_b32_e32 v4, 0xffff0000, v7
	v_and_b32_e32 v5, 0xffff0000, v73
	v_mul_f32_e32 v4, v4, v5
	v_cvt_pk_bf16_f32 v3, v3, v4
	v_lshlrev_b32_e32 v4, 16, v74
	v_lshlrev_b32_e32 v5, 16, v8
	v_mul_f32_e32 v4, v5, v4
	v_and_b32_e32 v5, 0xffff0000, v8
	v_and_b32_e32 v6, 0xffff0000, v74
	v_mul_f32_e32 v5, v5, v6
	v_cvt_pk_bf16_f32 v4, v4, v5
	v_lshlrev_b32_e32 v5, 16, v75
	v_lshlrev_b32_e32 v6, 16, v9
	v_mul_f32_e32 v5, v6, v5
	v_and_b32_e32 v6, 0xffff0000, v9
	v_and_b32_e32 v7, 0xffff0000, v75
	v_mul_f32_e32 v6, v6, v7
	v_cvt_pk_bf16_f32 v5, v5, v6
	ds_read_b128 v[6:9], v12 offset:6528
	global_store_dwordx4 v[10:11], v[2:5], off sc1
	v_lshlrev_b64 v[10:11], 13, v[98:99]
	v_lshl_add_u64 v[10:11], v[0:1], 0, v[10:11]
	s_waitcnt vmcnt(7)
	v_lshlrev_b32_e32 v2, 16, v68
	s_waitcnt lgkmcnt(0)
	v_lshlrev_b32_e32 v3, 16, v6
	v_mul_f32_e32 v2, v3, v2
	v_and_b32_e32 v3, 0xffff0000, v6
	v_and_b32_e32 v4, 0xffff0000, v68
	v_mul_f32_e32 v3, v3, v4
	v_cvt_pk_bf16_f32 v2, v2, v3
	v_lshlrev_b32_e32 v3, 16, v69
	v_lshlrev_b32_e32 v4, 16, v7
	v_mul_f32_e32 v3, v4, v3
	v_and_b32_e32 v4, 0xffff0000, v7
	v_and_b32_e32 v5, 0xffff0000, v69
	v_mul_f32_e32 v4, v4, v5
	v_cvt_pk_bf16_f32 v3, v3, v4
	v_lshlrev_b32_e32 v4, 16, v70
	v_lshlrev_b32_e32 v5, 16, v8
	v_mul_f32_e32 v4, v5, v4
	v_and_b32_e32 v5, 0xffff0000, v8
	v_and_b32_e32 v6, 0xffff0000, v70
	v_mul_f32_e32 v5, v5, v6
	v_cvt_pk_bf16_f32 v4, v4, v5
	v_lshlrev_b32_e32 v5, 16, v71
	v_lshlrev_b32_e32 v6, 16, v9
	v_mul_f32_e32 v5, v6, v5
	v_and_b32_e32 v6, 0xffff0000, v9
	v_and_b32_e32 v7, 0xffff0000, v71
	v_mul_f32_e32 v6, v6, v7
	v_cvt_pk_bf16_f32 v5, v5, v6
	ds_read_b128 v[6:9], v12 offset:7616
	global_store_dwordx4 v[10:11], v[2:5], off sc1
	v_readlane_b32 s2, v255, 50
	s_add_i32 s16, s16, s2
	s_waitcnt vmcnt(7)
	v_lshlrev_b32_e32 v2, 16, v64
	s_waitcnt lgkmcnt(0)
	v_lshlrev_b32_e32 v3, 16, v6
	v_mul_f32_e32 v2, v3, v2
	v_and_b32_e32 v3, 0xffff0000, v6
	v_and_b32_e32 v4, 0xffff0000, v64
	v_mul_f32_e32 v3, v3, v4
	v_cvt_pk_bf16_f32 v2, v2, v3
	v_lshlrev_b32_e32 v3, 16, v65
	v_lshlrev_b32_e32 v4, 16, v7
	v_mul_f32_e32 v3, v4, v3
	v_and_b32_e32 v4, 0xffff0000, v7
	v_and_b32_e32 v5, 0xffff0000, v65
	v_mul_f32_e32 v4, v4, v5
	v_cvt_pk_bf16_f32 v3, v3, v4
	v_lshlrev_b32_e32 v4, 16, v66
	v_lshlrev_b32_e32 v5, 16, v8
	v_mul_f32_e32 v4, v5, v4
	v_and_b32_e32 v5, 0xffff0000, v8
	v_and_b32_e32 v6, 0xffff0000, v66
	v_mul_f32_e32 v5, v5, v6
	v_cvt_pk_bf16_f32 v4, v4, v5
	v_lshlrev_b32_e32 v5, 16, v67
	v_lshlrev_b32_e32 v6, 16, v9
	v_mul_f32_e32 v5, v6, v5
	v_and_b32_e32 v6, 0xffff0000, v9
	v_and_b32_e32 v7, 0xffff0000, v67
	v_mul_f32_e32 v6, v6, v7
	v_cvt_pk_bf16_f32 v5, v5, v6
	v_lshlrev_b64 v[6:7], 13, v[96:97]
	v_lshl_add_u64 v[0:1], v[0:1], 0, v[6:7]
	s_cmp_ge_i32 s24, s89
	global_store_dwordx4 v[0:1], v[2:5], off sc1
	s_cbranch_scc1 .LBB0_728

.LBB0_770:
	v_mov_b32_e32 v138, v220
	s_lshl_b32 s27, s15, 8
	v_readfirstlane_b32 s26, v138
	s_ashr_i32 s28, s26, 2
	s_andn2_b32 s28, s28, 63
	s_lshr_b32 s26, s26, 1
	s_add_i32 s28, s28, s27
	s_lshl_b32 s27, s36, 7
	s_and_b32 s26, s26, 0x60
	v_and_or_b32 v140, v138, 15, s28
	s_or_b32 s26, s26, s27
	v_lshrrev_b32_e32 v138, 1, v138
	v_and_or_b32 v138, v138, 24, s26
	v_ashrrev_i32_e32 v139, 31, v138
	v_mov_b64_e32 v[142:143], s[4:5]
	v_mad_i64_i32 v[146:147], s[26:27], v140, s45, v[142:143]
	v_lshlrev_b64 v[138:139], 1, v[138:139]
	v_lshl_add_u64 v[146:147], v[146:147], 0, v[138:139]
	v_add_co_u32_e32 v146, vcc, s47, v146
	v_mul_f32_e32 v116, 0xbfb8aa3b, v116
	s_nop 0
	v_addc_co_u32_e32 v147, vcc, 0, v147, vcc
	global_load_dwordx4 v[146:149], v[146:147], off
	v_exp_f32_e32 v116, v116
	v_mul_f32_e32 v117, 0xbfb8aa3b, v117
	v_exp_f32_e32 v117, v117
	v_mul_f32_e32 v118, 0xbfb8aa3b, v118
	v_exp_f32_e32 v118, v118
	v_add_f32_e32 v116, 1.0, v116
	v_rcp_f32_e32 v116, v116
	v_add_f32_e32 v117, 1.0, v117
	v_rcp_f32_e32 v117, v117
	v_add_f32_e32 v118, 1.0, v118
	v_rcp_f32_e32 v118, v118
	v_mul_f32_e32 v120, 0xbfb8aa3b, v120
	v_mul_f32_e32 v119, 0xbfb8aa3b, v119
	v_exp_f32_e32 v120, v120
	v_mul_f32_e32 v112, v116, v112
	v_mul_f32_e32 v116, 0xbfb8aa3b, v121
	v_exp_f32_e32 v119, v119
	v_exp_f32_e32 v116, v116
	v_mul_f32_e32 v113, v117, v113
	v_mul_f32_e32 v117, 0xbfb8aa3b, v122
	v_exp_f32_e32 v117, v117
	v_mul_f32_e32 v114, v118, v114
	v_mul_f32_e32 v118, 0xbfb8aa3b, v123
	v_exp_f32_e32 v118, v118
	v_add_f32_e32 v120, 1.0, v120
	v_add_f32_e32 v119, 1.0, v119
	v_rcp_f32_e32 v120, v120
	v_add_f32_e32 v116, 1.0, v116
	v_rcp_f32_e32 v119, v119
	v_rcp_f32_e32 v116, v116
	v_add_f32_e32 v117, 1.0, v117
	v_rcp_f32_e32 v117, v117
	v_add_f32_e32 v118, 1.0, v118
	v_rcp_f32_e32 v118, v118
	v_mul_f32_e32 v120, v120, v124
	v_mul_f32_e32 v115, v119, v115
	v_mul_f32_e32 v116, v116, v125
	v_mul_f32_e32 v117, v117, v126
	v_mul_f32_e32 v118, v118, v127
	v_ashrrev_i32_e32 v141, 31, v140
	v_mul_f32_e32 v100, 0xbfb8aa3b, v100
	v_exp_f32_e32 v100, v100
	v_mul_f32_e32 v101, 0xbfb8aa3b, v101
	v_exp_f32_e32 v101, v101
	v_mul_f32_e32 v102, 0xbfb8aa3b, v102
	v_exp_f32_e32 v102, v102
	v_add_f32_e32 v100, 1.0, v100
	v_rcp_f32_e32 v100, v100
	v_add_f32_e32 v101, 1.0, v101
	v_rcp_f32_e32 v101, v101
	v_add_f32_e32 v102, 1.0, v102
	v_rcp_f32_e32 v102, v102
	v_mul_f32_e32 v104, 0xbfb8aa3b, v104
	v_mul_f32_e32 v103, 0xbfb8aa3b, v103
	v_exp_f32_e32 v104, v104
	v_mul_f32_e32 v96, v100, v96
	v_mul_f32_e32 v100, 0xbfb8aa3b, v105
	v_exp_f32_e32 v103, v103
	v_exp_f32_e32 v100, v100
	v_mul_f32_e32 v97, v101, v97
	v_mul_f32_e32 v101, 0xbfb8aa3b, v106
	v_exp_f32_e32 v101, v101
	v_mul_f32_e32 v98, v102, v98
	v_mul_f32_e32 v102, 0xbfb8aa3b, v107
	v_exp_f32_e32 v102, v102
	v_add_f32_e32 v104, 1.0, v104
	v_add_f32_e32 v103, 1.0, v103
	v_rcp_f32_e32 v104, v104
	v_add_f32_e32 v100, 1.0, v100
	v_rcp_f32_e32 v103, v103
	v_rcp_f32_e32 v100, v100
	v_add_f32_e32 v101, 1.0, v101
	v_rcp_f32_e32 v101, v101
	v_add_f32_e32 v102, 1.0, v102
	v_rcp_f32_e32 v102, v102
	v_mul_f32_e32 v104, v104, v108
	v_mul_f32_e32 v99, v103, v99
	v_mul_f32_e32 v100, v100, v109
	v_mul_f32_e32 v101, v101, v110
	s_waitcnt vmcnt(0)
	v_lshlrev_b32_e32 v119, 16, v146
	v_mul_f32_e32 v119, v120, v119
	v_and_b32_e32 v120, 0xffff0000, v146
	v_mul_f32_e32 v116, v116, v120
	v_lshlrev_b32_e32 v120, 16, v147
	v_mul_f32_e32 v117, v117, v120
	v_and_b32_e32 v120, 0xffff0000, v147
	v_mul_f32_e32 v118, v118, v120
	v_lshlrev_b32_e32 v120, 16, v148
	v_mul_f32_e32 v120, v112, v120
	v_and_b32_e32 v112, 0xffff0000, v148
	v_mul_f32_e32 v121, v113, v112
	v_lshlrev_b32_e32 v112, 16, v149
	v_mul_f32_e32 v122, v114, v112
	v_and_b32_e32 v112, 0xffff0000, v149
	v_mul_f32_e32 v115, v115, v112
	v_cvt_pk_bf16_f32 v112, v119, v116
	v_cvt_pk_bf16_f32 v113, v117, v118
	v_lshlrev_b64 v[116:117], 13, v[140:141]
	v_lshl_add_u64 v[116:117], s[6:7], 0, v[116:117]
	v_lshl_add_u64 v[116:117], v[116:117], 0, v[138:139]
	v_add_co_u32_e32 v116, vcc, s46, v116
	v_cvt_pk_bf16_f32 v114, v120, v121
	v_cvt_pk_bf16_f32 v115, v122, v115
	v_mul_f32_e32 v102, v102, v111
	s_nop 0
	v_addc_co_u32_e32 v117, vcc, 0, v117, vcc
	global_store_dwordx4 v[116:117], v[112:115], off sc1
	v_mul_f32_e32 v84, 0xbfb8aa3b, v84
	v_exp_f32_e32 v84, v84
	v_or_b32_e32 v112, 16, v140
	v_mad_i64_i32 v[114:115], s[26:27], v112, s45, v[142:143]
	v_lshl_add_u64 v[114:115], v[114:115], 0, v[138:139]
	v_add_co_u32_e32 v114, vcc, s47, v114
	v_ashrrev_i32_e32 v113, 31, v112
	s_nop 0
	v_addc_co_u32_e32 v115, vcc, 0, v115, vcc
	global_load_dwordx4 v[114:117], v[114:115], off
	v_mul_f32_e32 v85, 0xbfb8aa3b, v85
	v_exp_f32_e32 v85, v85
	v_mul_f32_e32 v86, 0xbfb8aa3b, v86
	v_exp_f32_e32 v86, v86
	v_add_f32_e32 v84, 1.0, v84
	v_rcp_f32_e32 v84, v84
	v_add_f32_e32 v85, 1.0, v85
	v_rcp_f32_e32 v85, v85
	v_add_f32_e32 v86, 1.0, v86
	v_rcp_f32_e32 v86, v86
	v_mul_f32_e32 v88, 0xbfb8aa3b, v88
	v_mul_f32_e32 v87, 0xbfb8aa3b, v87
	v_exp_f32_e32 v88, v88
	v_mul_f32_e32 v80, v84, v80
	v_mul_f32_e32 v84, 0xbfb8aa3b, v89
	v_exp_f32_e32 v87, v87
	v_exp_f32_e32 v84, v84
	v_mul_f32_e32 v81, v85, v81
	v_mul_f32_e32 v85, 0xbfb8aa3b, v90
	v_exp_f32_e32 v85, v85
	v_mul_f32_e32 v82, v86, v82
	v_mul_f32_e32 v86, 0xbfb8aa3b, v91
	v_exp_f32_e32 v86, v86
	v_add_f32_e32 v88, 1.0, v88
	v_add_f32_e32 v87, 1.0, v87
	v_rcp_f32_e32 v88, v88
	v_add_f32_e32 v84, 1.0, v84
	v_rcp_f32_e32 v87, v87
	v_rcp_f32_e32 v84, v84
	v_add_f32_e32 v85, 1.0, v85
	v_rcp_f32_e32 v85, v85
	v_add_f32_e32 v86, 1.0, v86
	v_rcp_f32_e32 v86, v86
	v_mul_f32_e32 v88, v88, v92
	v_mul_f32_e32 v83, v87, v83
	v_mul_f32_e32 v84, v84, v93
	v_mul_f32_e32 v85, v85, v94
	v_mul_f32_e32 v86, v86, v95
	v_mul_f32_e32 v68, 0xbfb8aa3b, v68
	v_exp_f32_e32 v68, v68
	v_mul_f32_e32 v69, 0xbfb8aa3b, v69
	v_exp_f32_e32 v69, v69
	v_mul_f32_e32 v70, 0xbfb8aa3b, v70
	v_exp_f32_e32 v70, v70
	v_add_f32_e32 v68, 1.0, v68
	v_rcp_f32_e32 v68, v68
	v_add_f32_e32 v69, 1.0, v69
	v_rcp_f32_e32 v69, v69
	v_add_f32_e32 v70, 1.0, v70
	v_rcp_f32_e32 v70, v70
	v_mul_f32_e32 v72, 0xbfb8aa3b, v72
	v_mul_f32_e32 v71, 0xbfb8aa3b, v71
	v_exp_f32_e32 v72, v72
	v_mul_f32_e32 v64, v68, v64
	v_mul_f32_e32 v68, 0xbfb8aa3b, v73
	v_exp_f32_e32 v71, v71
	v_exp_f32_e32 v68, v68
	v_mul_f32_e32 v65, v69, v65
	v_mul_f32_e32 v69, 0xbfb8aa3b, v74
	v_exp_f32_e32 v69, v69
	v_mul_f32_e32 v66, v70, v66
	v_mul_f32_e32 v70, 0xbfb8aa3b, v75
	v_exp_f32_e32 v70, v70
	v_add_f32_e32 v72, 1.0, v72
	v_add_f32_e32 v71, 1.0, v71
	v_rcp_f32_e32 v72, v72
	v_add_f32_e32 v68, 1.0, v68
	v_rcp_f32_e32 v71, v71
	v_rcp_f32_e32 v68, v68
	v_add_f32_e32 v69, 1.0, v69
	v_rcp_f32_e32 v69, v69
	v_add_f32_e32 v70, 1.0, v70
	v_rcp_f32_e32 v70, v70
	v_mul_f32_e32 v72, v72, v76
	v_mul_f32_e32 v67, v71, v67
	v_mul_f32_e32 v68, v68, v77
	v_mul_f32_e32 v69, v69, v78
	v_mul_f32_e32 v70, v70, v79
	v_mul_f32_e32 v52, 0xbfb8aa3b, v52
	s_waitcnt vmcnt(0)
	v_lshlrev_b32_e32 v103, 16, v114
	v_mul_f32_e32 v103, v104, v103
	v_and_b32_e32 v104, 0xffff0000, v114
	v_mul_f32_e32 v100, v100, v104
	v_lshlrev_b32_e32 v104, 16, v115
	v_mul_f32_e32 v101, v101, v104
	v_and_b32_e32 v104, 0xffff0000, v115
	v_mul_f32_e32 v102, v102, v104
	v_lshlrev_b32_e32 v104, 16, v116
	v_mul_f32_e32 v104, v96, v104
	v_and_b32_e32 v96, 0xffff0000, v116
	v_mul_f32_e32 v105, v97, v96
	v_lshlrev_b32_e32 v96, 16, v117
	v_mul_f32_e32 v106, v98, v96
	v_and_b32_e32 v96, 0xffff0000, v117
	v_mul_f32_e32 v99, v99, v96
	v_cvt_pk_bf16_f32 v96, v103, v100
	v_cvt_pk_bf16_f32 v97, v101, v102
	v_lshlrev_b64 v[100:101], 13, v[112:113]
	v_lshl_add_u64 v[100:101], s[6:7], 0, v[100:101]
	v_lshl_add_u64 v[100:101], v[100:101], 0, v[138:139]
	v_add_co_u32_e32 v100, vcc, s46, v100
	v_cvt_pk_bf16_f32 v98, v104, v105
	v_cvt_pk_bf16_f32 v99, v106, v99
	v_exp_f32_e32 v52, v52
	s_nop 0
	v_addc_co_u32_e32 v101, vcc, 0, v101, vcc
	global_store_dwordx4 v[100:101], v[96:99], off sc1
	v_mul_f32_e32 v53, 0xbfb8aa3b, v53
	v_exp_f32_e32 v53, v53
	v_or_b32_e32 v96, 32, v140
	v_mad_i64_i32 v[98:99], s[26:27], v96, s45, v[142:143]
	v_lshl_add_u64 v[98:99], v[98:99], 0, v[138:139]
	v_add_co_u32_e32 v98, vcc, s47, v98
	v_ashrrev_i32_e32 v97, 31, v96
	s_nop 0
	v_addc_co_u32_e32 v99, vcc, 0, v99, vcc
	global_load_dwordx4 v[98:101], v[98:99], off
	v_mul_f32_e32 v54, 0xbfb8aa3b, v54
	v_exp_f32_e32 v54, v54
	v_add_f32_e32 v52, 1.0, v52
	v_rcp_f32_e32 v52, v52
	v_add_f32_e32 v53, 1.0, v53
	v_rcp_f32_e32 v53, v53
	v_add_f32_e32 v54, 1.0, v54
	v_rcp_f32_e32 v54, v54
	v_mul_f32_e32 v56, 0xbfb8aa3b, v56
	v_mul_f32_e32 v55, 0xbfb8aa3b, v55
	v_exp_f32_e32 v56, v56
	v_mul_f32_e32 v48, v52, v48
	v_mul_f32_e32 v52, 0xbfb8aa3b, v57
	v_exp_f32_e32 v55, v55
	v_exp_f32_e32 v52, v52
	v_mul_f32_e32 v49, v53, v49
	v_mul_f32_e32 v53, 0xbfb8aa3b, v58
	v_exp_f32_e32 v53, v53
	v_mul_f32_e32 v50, v54, v50
	v_mul_f32_e32 v54, 0xbfb8aa3b, v59
	v_exp_f32_e32 v54, v54
	v_add_f32_e32 v56, 1.0, v56
	v_add_f32_e32 v55, 1.0, v55
	v_rcp_f32_e32 v56, v56
	v_add_f32_e32 v52, 1.0, v52
	v_rcp_f32_e32 v55, v55
	v_rcp_f32_e32 v52, v52
	v_add_f32_e32 v53, 1.0, v53
	v_rcp_f32_e32 v53, v53
	v_add_f32_e32 v54, 1.0, v54
	v_rcp_f32_e32 v54, v54
	v_mul_f32_e32 v56, v56, v60
	v_mul_f32_e32 v51, v55, v51
	v_mul_f32_e32 v52, v52, v61
	v_mul_f32_e32 v53, v53, v62
	v_mul_f32_e32 v54, v54, v63
	v_mul_f32_e32 v36, 0xbfb8aa3b, v36
	v_exp_f32_e32 v36, v36
	v_mul_f32_e32 v37, 0xbfb8aa3b, v37
	v_exp_f32_e32 v37, v37
	v_mul_f32_e32 v38, 0xbfb8aa3b, v38
	v_exp_f32_e32 v38, v38
	v_add_f32_e32 v36, 1.0, v36
	v_rcp_f32_e32 v36, v36
	v_add_f32_e32 v37, 1.0, v37
	v_rcp_f32_e32 v37, v37
	v_add_f32_e32 v38, 1.0, v38
	v_rcp_f32_e32 v38, v38
	v_mul_f32_e32 v40, 0xbfb8aa3b, v40
	v_mul_f32_e32 v39, 0xbfb8aa3b, v39
	v_exp_f32_e32 v40, v40
	v_mul_f32_e32 v32, v36, v32
	v_mul_f32_e32 v36, 0xbfb8aa3b, v41
	v_exp_f32_e32 v39, v39
	v_exp_f32_e32 v36, v36
	v_mul_f32_e32 v33, v37, v33
	v_mul_f32_e32 v37, 0xbfb8aa3b, v42
	v_exp_f32_e32 v37, v37
	v_mul_f32_e32 v34, v38, v34
	v_mul_f32_e32 v38, 0xbfb8aa3b, v43
	v_exp_f32_e32 v38, v38
	v_add_f32_e32 v40, 1.0, v40
	v_add_f32_e32 v39, 1.0, v39
	v_rcp_f32_e32 v40, v40
	v_add_f32_e32 v36, 1.0, v36
	v_rcp_f32_e32 v39, v39
	v_rcp_f32_e32 v36, v36
	v_add_f32_e32 v37, 1.0, v37
	v_rcp_f32_e32 v37, v37
	v_add_f32_e32 v38, 1.0, v38
	v_rcp_f32_e32 v38, v38
	v_mul_f32_e32 v40, v40, v44
	v_mul_f32_e32 v35, v39, v35
	v_mul_f32_e32 v36, v36, v45
	v_mul_f32_e32 v37, v37, v46
	v_mul_f32_e32 v38, v38, v47
	v_mul_f32_e32 v20, 0xbfb8aa3b, v20
	v_exp_f32_e32 v20, v20
	v_mul_f32_e32 v21, 0xbfb8aa3b, v21
	s_waitcnt vmcnt(0)
	v_lshlrev_b32_e32 v87, 16, v98
	v_mul_f32_e32 v87, v88, v87
	v_and_b32_e32 v88, 0xffff0000, v98
	v_mul_f32_e32 v84, v84, v88
	v_lshlrev_b32_e32 v88, 16, v99
	v_mul_f32_e32 v85, v85, v88
	v_and_b32_e32 v88, 0xffff0000, v99
	v_mul_f32_e32 v86, v86, v88
	v_lshlrev_b32_e32 v88, 16, v100
	v_mul_f32_e32 v88, v80, v88
	v_and_b32_e32 v80, 0xffff0000, v100
	v_mul_f32_e32 v89, v81, v80
	v_lshlrev_b32_e32 v80, 16, v101
	v_mul_f32_e32 v90, v82, v80
	v_and_b32_e32 v80, 0xffff0000, v101
	v_mul_f32_e32 v83, v83, v80
	v_cvt_pk_bf16_f32 v80, v87, v84
	v_cvt_pk_bf16_f32 v81, v85, v86
	v_lshlrev_b64 v[84:85], 13, v[96:97]
	v_lshl_add_u64 v[84:85], s[6:7], 0, v[84:85]
	v_lshl_add_u64 v[84:85], v[84:85], 0, v[138:139]
	v_add_co_u32_e32 v84, vcc, s46, v84
	v_cvt_pk_bf16_f32 v82, v88, v89
	v_cvt_pk_bf16_f32 v83, v90, v83
	v_exp_f32_e32 v21, v21
	s_nop 0
	v_addc_co_u32_e32 v85, vcc, 0, v85, vcc
	global_store_dwordx4 v[84:85], v[80:83], off sc1
	v_mul_f32_e32 v22, 0xbfb8aa3b, v22
	v_exp_f32_e32 v22, v22
	v_or_b32_e32 v80, 48, v140
	v_mad_i64_i32 v[82:83], s[26:27], v80, s45, v[142:143]
	v_lshl_add_u64 v[82:83], v[82:83], 0, v[138:139]
	v_add_co_u32_e32 v82, vcc, s47, v82
	v_ashrrev_i32_e32 v81, 31, v80
	s_nop 0
	v_addc_co_u32_e32 v83, vcc, 0, v83, vcc
	global_load_dwordx4 v[82:85], v[82:83], off
	v_add_f32_e32 v20, 1.0, v20
	v_rcp_f32_e32 v20, v20
	v_add_f32_e32 v21, 1.0, v21
	v_rcp_f32_e32 v21, v21
	v_add_f32_e32 v22, 1.0, v22
	v_rcp_f32_e32 v22, v22
	v_mul_f32_e32 v24, 0xbfb8aa3b, v24
	v_mul_f32_e32 v23, 0xbfb8aa3b, v23
	v_exp_f32_e32 v24, v24
	v_mul_f32_e32 v16, v20, v16
	v_mul_f32_e32 v20, 0xbfb8aa3b, v25
	v_exp_f32_e32 v23, v23
	v_exp_f32_e32 v20, v20
	v_mul_f32_e32 v17, v21, v17
	v_mul_f32_e32 v21, 0xbfb8aa3b, v26
	v_exp_f32_e32 v21, v21
	v_mul_f32_e32 v18, v22, v18
	v_mul_f32_e32 v22, 0xbfb8aa3b, v27
	v_exp_f32_e32 v22, v22
	v_add_f32_e32 v24, 1.0, v24
	v_add_f32_e32 v23, 1.0, v23
	v_rcp_f32_e32 v24, v24
	v_add_f32_e32 v20, 1.0, v20
	v_rcp_f32_e32 v23, v23
	v_rcp_f32_e32 v20, v20
	v_add_f32_e32 v21, 1.0, v21
	v_rcp_f32_e32 v21, v21
	v_add_f32_e32 v22, 1.0, v22
	v_rcp_f32_e32 v22, v22
	v_mul_f32_e32 v24, v24, v28
	v_mul_f32_e32 v19, v23, v19
	v_mul_f32_e32 v20, v20, v29
	v_mul_f32_e32 v21, v21, v30
	v_mul_f32_e32 v22, v22, v31
	v_mul_f32_e32 v4, 0xbfb8aa3b, v4
	v_mul_f32_e32 v0, 0xbfb8aa3b, v0
	v_exp_f32_e32 v4, v4
	v_exp_f32_e32 v0, v0
	v_mul_f32_e32 v5, 0xbfb8aa3b, v5
	v_exp_f32_e32 v5, v5
	v_mul_f32_e32 v6, 0xbfb8aa3b, v6
	v_exp_f32_e32 v6, v6
	v_mul_f32_e32 v7, 0xbfb8aa3b, v7
	v_exp_f32_e32 v7, v7
	v_add_f32_e32 v4, 1.0, v4
	v_add_f32_e32 v0, 1.0, v0
	v_mul_f32_e32 v1, 0xbfb8aa3b, v1
	v_rcp_f32_e32 v4, v4
	v_rcp_f32_e32 v0, v0
	v_add_f32_e32 v5, 1.0, v5
	v_exp_f32_e32 v1, v1
	v_mul_f32_e32 v2, 0xbfb8aa3b, v2
	v_rcp_f32_e32 v5, v5
	v_add_f32_e32 v6, 1.0, v6
	v_exp_f32_e32 v2, v2
	v_mul_f32_e32 v3, 0xbfb8aa3b, v3
	v_rcp_f32_e32 v6, v6
	v_add_f32_e32 v7, 1.0, v7
	v_exp_f32_e32 v3, v3
	v_rcp_f32_e32 v7, v7
	v_mul_f32_e32 v4, v4, v12
	v_mul_f32_e32 v0, v0, v8
	v_add_f32_e32 v1, 1.0, v1
	v_mul_f32_e32 v5, v5, v13
	v_rcp_f32_e32 v1, v1
	v_add_f32_e32 v2, 1.0, v2
	v_mul_f32_e32 v6, v6, v14
	v_rcp_f32_e32 v2, v2
	v_add_f32_e32 v3, 1.0, v3
	v_mul_f32_e32 v7, v7, v15
	v_rcp_f32_e32 v3, v3
	v_mul_f32_e32 v1, v1, v9
	v_mul_f32_e32 v2, v2, v10
	v_mul_f32_e32 v3, v3, v11
	s_waitcnt vmcnt(0)
	v_lshlrev_b32_e32 v71, 16, v82
	v_mul_f32_e32 v71, v72, v71
	v_and_b32_e32 v72, 0xffff0000, v82
	v_mul_f32_e32 v68, v68, v72
	v_lshlrev_b32_e32 v72, 16, v83
	v_mul_f32_e32 v69, v69, v72
	v_and_b32_e32 v72, 0xffff0000, v83
	v_mul_f32_e32 v70, v70, v72
	v_lshlrev_b32_e32 v72, 16, v84
	v_mul_f32_e32 v72, v64, v72
	v_and_b32_e32 v64, 0xffff0000, v84
	v_mul_f32_e32 v73, v65, v64
	v_lshlrev_b32_e32 v64, 16, v85
	v_mul_f32_e32 v74, v66, v64
	v_and_b32_e32 v64, 0xffff0000, v85
	v_mul_f32_e32 v67, v67, v64
	v_cvt_pk_bf16_f32 v64, v71, v68
	v_cvt_pk_bf16_f32 v65, v69, v70
	v_lshlrev_b64 v[68:69], 13, v[80:81]
	v_lshl_add_u64 v[68:69], s[6:7], 0, v[68:69]
	v_lshl_add_u64 v[68:69], v[68:69], 0, v[138:139]
	v_add_co_u32_e32 v68, vcc, s46, v68
	v_cvt_pk_bf16_f32 v66, v72, v73
	v_cvt_pk_bf16_f32 v67, v74, v67
	s_nop 1
	v_addc_co_u32_e32 v69, vcc, 0, v69, vcc
	global_store_dwordx4 v[68:69], v[64:67], off sc1
	s_nop 1
	v_add_u32_e32 v64, 0x80, v140
	v_mad_i64_i32 v[66:67], s[26:27], v64, s45, v[142:143]
	v_lshl_add_u64 v[66:67], v[66:67], 0, v[138:139]
	v_add_co_u32_e32 v66, vcc, s47, v66
	v_ashrrev_i32_e32 v65, 31, v64
	s_nop 0
	v_addc_co_u32_e32 v67, vcc, 0, v67, vcc
	global_load_dwordx4 v[66:69], v[66:67], off
	s_waitcnt vmcnt(0)
	v_lshlrev_b32_e32 v55, 16, v66
	v_mul_f32_e32 v55, v56, v55
	v_and_b32_e32 v56, 0xffff0000, v66
	v_mul_f32_e32 v52, v52, v56
	v_lshlrev_b32_e32 v56, 16, v67
	v_mul_f32_e32 v53, v53, v56
	v_and_b32_e32 v56, 0xffff0000, v67
	v_mul_f32_e32 v54, v54, v56
	v_lshlrev_b32_e32 v56, 16, v68
	v_mul_f32_e32 v56, v48, v56
	v_and_b32_e32 v48, 0xffff0000, v68
	v_mul_f32_e32 v57, v49, v48
	v_lshlrev_b32_e32 v48, 16, v69
	v_mul_f32_e32 v58, v50, v48
	v_and_b32_e32 v48, 0xffff0000, v69
	v_mul_f32_e32 v51, v51, v48
	v_cvt_pk_bf16_f32 v48, v55, v52
	v_cvt_pk_bf16_f32 v49, v53, v54
	v_lshlrev_b64 v[52:53], 13, v[64:65]
	v_lshl_add_u64 v[52:53], s[6:7], 0, v[52:53]
	v_lshl_add_u64 v[52:53], v[52:53], 0, v[138:139]
	v_add_co_u32_e32 v52, vcc, s46, v52
	v_cvt_pk_bf16_f32 v50, v56, v57
	v_cvt_pk_bf16_f32 v51, v58, v51
	s_nop 1
	v_addc_co_u32_e32 v53, vcc, 0, v53, vcc
	global_store_dwordx4 v[52:53], v[48:51], off sc1
	s_nop 1
	v_add_u32_e32 v48, 0x90, v140
	v_mad_i64_i32 v[50:51], s[26:27], v48, s45, v[142:143]
	v_lshl_add_u64 v[50:51], v[50:51], 0, v[138:139]
	v_add_co_u32_e32 v50, vcc, s47, v50
	v_ashrrev_i32_e32 v49, 31, v48
	s_nop 0
	v_addc_co_u32_e32 v51, vcc, 0, v51, vcc
	global_load_dwordx4 v[50:53], v[50:51], off
	s_waitcnt vmcnt(0)
	v_lshlrev_b32_e32 v39, 16, v50
	v_mul_f32_e32 v39, v40, v39
	v_and_b32_e32 v40, 0xffff0000, v50
	v_mul_f32_e32 v36, v36, v40
	v_lshlrev_b32_e32 v40, 16, v51
	v_mul_f32_e32 v37, v37, v40
	v_and_b32_e32 v40, 0xffff0000, v51
	v_mul_f32_e32 v38, v38, v40
	v_lshlrev_b32_e32 v40, 16, v52
	v_mul_f32_e32 v40, v32, v40
	v_and_b32_e32 v32, 0xffff0000, v52
	v_mul_f32_e32 v41, v33, v32
	v_lshlrev_b32_e32 v32, 16, v53
	v_mul_f32_e32 v42, v34, v32
	v_and_b32_e32 v32, 0xffff0000, v53
	v_mul_f32_e32 v35, v35, v32
	v_cvt_pk_bf16_f32 v32, v39, v36
	v_cvt_pk_bf16_f32 v33, v37, v38
	v_lshlrev_b64 v[36:37], 13, v[48:49]
	v_lshl_add_u64 v[36:37], s[6:7], 0, v[36:37]
	v_lshl_add_u64 v[36:37], v[36:37], 0, v[138:139]
	v_add_co_u32_e32 v36, vcc, s46, v36
	v_cvt_pk_bf16_f32 v34, v40, v41
	v_cvt_pk_bf16_f32 v35, v42, v35
	s_nop 1
	v_addc_co_u32_e32 v37, vcc, 0, v37, vcc
	global_store_dwordx4 v[36:37], v[32:35], off sc1
	s_nop 1
	v_add_u32_e32 v32, 0xa0, v140
	v_mad_i64_i32 v[34:35], s[26:27], v32, s45, v[142:143]
	v_lshl_add_u64 v[34:35], v[34:35], 0, v[138:139]
	v_add_co_u32_e32 v34, vcc, s47, v34
	v_ashrrev_i32_e32 v33, 31, v32
	s_nop 0
	v_addc_co_u32_e32 v35, vcc, 0, v35, vcc
	global_load_dwordx4 v[34:37], v[34:35], off
	s_waitcnt vmcnt(0)
	v_lshlrev_b32_e32 v23, 16, v34
	v_mul_f32_e32 v23, v24, v23
	v_and_b32_e32 v24, 0xffff0000, v34
	v_mul_f32_e32 v20, v20, v24
	v_lshlrev_b32_e32 v24, 16, v35
	v_mul_f32_e32 v21, v21, v24
	v_and_b32_e32 v24, 0xffff0000, v35
	v_mul_f32_e32 v22, v22, v24
	v_lshlrev_b32_e32 v24, 16, v36
	v_mul_f32_e32 v24, v16, v24
	v_and_b32_e32 v16, 0xffff0000, v36
	v_mul_f32_e32 v25, v17, v16
	v_lshlrev_b32_e32 v16, 16, v37
	v_mul_f32_e32 v26, v18, v16
	v_and_b32_e32 v16, 0xffff0000, v37
	v_mul_f32_e32 v19, v19, v16
	v_cvt_pk_bf16_f32 v16, v23, v20
	v_cvt_pk_bf16_f32 v17, v21, v22
	v_lshlrev_b64 v[20:21], 13, v[32:33]
	v_lshl_add_u64 v[20:21], s[6:7], 0, v[20:21]
	v_lshl_add_u64 v[20:21], v[20:21], 0, v[138:139]
	v_add_co_u32_e32 v20, vcc, s46, v20
	v_cvt_pk_bf16_f32 v18, v24, v25
	v_cvt_pk_bf16_f32 v19, v26, v19
	s_nop 1
	v_addc_co_u32_e32 v21, vcc, 0, v21, vcc
	global_store_dwordx4 v[20:21], v[16:19], off sc1
	s_nop 1
	v_add_u32_e32 v16, 0xb0, v140
	v_mad_i64_i32 v[18:19], s[26:27], v16, s45, v[142:143]
	v_lshl_add_u64 v[18:19], v[18:19], 0, v[138:139]
	v_add_co_u32_e32 v18, vcc, s47, v18
	v_ashrrev_i32_e32 v17, 31, v16
	s_nop 0
	v_addc_co_u32_e32 v19, vcc, 0, v19, vcc
	global_load_dwordx4 v[18:21], v[18:19], off
	s_mov_b64 s[26:27], -1
	s_waitcnt vmcnt(0)
	v_lshlrev_b32_e32 v8, 16, v18
	v_mul_f32_e32 v4, v4, v8
	v_and_b32_e32 v8, 0xffff0000, v18
	v_mul_f32_e32 v5, v5, v8
	v_lshlrev_b32_e32 v8, 16, v19
	v_mul_f32_e32 v6, v6, v8
	v_and_b32_e32 v8, 0xffff0000, v19
	v_mul_f32_e32 v7, v7, v8
	v_lshlrev_b32_e32 v8, 16, v20
	v_mul_f32_e32 v8, v0, v8
	v_and_b32_e32 v0, 0xffff0000, v20
	v_mul_f32_e32 v9, v1, v0
	v_lshlrev_b32_e32 v0, 16, v21
	v_mul_f32_e32 v10, v2, v0
	v_and_b32_e32 v0, 0xffff0000, v21
	v_mul_f32_e32 v3, v3, v0
	v_cvt_pk_bf16_f32 v0, v4, v5
	v_lshlrev_b64 v[4:5], 13, v[16:17]
	v_lshl_add_u64 v[4:5], s[6:7], 0, v[4:5]
	v_lshl_add_u64 v[4:5], v[4:5], 0, v[138:139]
	v_add_co_u32_e32 v4, vcc, 0x1000, v4
	v_cvt_pk_bf16_f32 v1, v6, v7
	v_cvt_pk_bf16_f32 v2, v8, v9
	v_cvt_pk_bf16_f32 v3, v10, v3
	s_nop 1
	v_addc_co_u32_e32 v5, vcc, 0, v5, vcc
	s_andn2_b64 vcc, exec, s[24:25]
	global_store_dwordx4 v[4:5], v[0:3], off sc1
	s_cbranch_vccnz .LBB0_753
	s_andn2_b64 vcc, exec, s[2:3]
	s_cbranch_vccnz .LBB0_752
	s_barrier
	s_branch .LBB0_752

.LBB0_790:
	v_readlane_b32 s4, v255, 14
	v_readlane_b32 s5, v255, 15
	v_cvt_f32_u32_e32 v1, v2
	v_sub_u32_e32 v4, 0, v2
	v_rcp_iflag_f32_e32 v1, v1
	s_nop 1
	buffer_wbl2 sc1
	s_waitcnt vmcnt(0)
	global_atomic_add v3, v177, v223, s[4:5] sc0
	v_mul_f32_e32 v1, 0x4f7ffffe, v1
	v_cvt_u32_f32_e32 v1, v1
	v_mul_lo_u32 v4, v4, v1
	v_mul_hi_u32 v4, v1, v4
	v_add_u32_e32 v1, v1, v4
	s_waitcnt vmcnt(0)
	v_mul_hi_u32 v1, v3, v1
	v_mul_lo_u32 v4, v1, v2
	v_sub_u32_e32 v4, v3, v4
	v_add_u32_e32 v5, 1, v1
	v_cmp_ge_u32_e32 vcc, v4, v2
	v_add_u32_e32 v3, 1, v3
	s_nop 0
	v_cndmask_b32_e32 v1, v1, v5, vcc
	v_sub_u32_e32 v5, v4, v2
	v_cndmask_b32_e32 v4, v4, v5, vcc
	v_add_u32_e32 v5, 1, v1
	v_cmp_ge_u32_e32 vcc, v4, v2
	s_nop 1
	v_cndmask_b32_e32 v1, v1, v5, vcc
	v_mul_lo_u32 v4, v2, v1
	v_add_u32_e32 v2, v4, v2
	v_cmp_ne_u32_e32 vcc, v3, v2
	s_and_saveexec_b64 s[4:5], vcc
	s_xor_b64 s[4:5], exec, s[4:5]
	s_cbranch_execz .LBB0_804
	v_readlane_b32 s6, v255, 16
	v_readlane_b32 s7, v255, 17
	s_waitcnt lgkmcnt(0)
	s_nop 3
	global_load_dword v0, v177, s[6:7] sc1
	s_waitcnt vmcnt(0)
	v_cmp_eq_u32_e32 vcc, v0, v1
	s_and_saveexec_b64 s[6:7], vcc
	s_cbranch_execz .LBB0_803
	s_mov_b32 s8, 1
	s_mov_b64 s[18:19], 0
	s_branch .LBB0_794
